# baseline (speedup 1.0000x reference)
; __device__ __forceinline__ int widen_off(int fq) { return ((fq & 1) << 4) + ((fq >> 1) << 3); }
; template <int NW>
; __device__ __forceinline__ void attn_item(const Params& p, int seq_t0, int L, int h, int q0, unsigned char* smem,
;                                           const int tid) {
;     ...
; #pragma unroll
;   for (int rs = 0; rs < 2; ++rs) {
;     float l = red_fq(lrun[rs]);
;     float inv = 1.0f / l;
;     const int t = q0 + wid * 32 + rs * 16 + fr;
; #pragma unroll
;     for (int dp = 0; dp < 2; ++dp) {
;       const bf16x4 a = pack4(o[rs][2 * dp][0] * inv, o[rs][2 * dp][1] * inv, o[rs][2 * dp][2] * inv, o[rs][2 * dp][3] * inv);
;       const bf16x4 b = pack4(o[rs][2 * dp + 1][0] * inv, o[rs][2 * dp + 1][1] * inv, o[rs][2 * dp + 1][2] * inv,
;                              o[rs][2 * dp + 1][3] * inv);
;       __builtin_nontemporal_store(widen_pair(a, b), reinterpret_cast<u32x4*>(p.mix + blk(t, 512 + h * 64 + dp * 32 + widen_off(fq), 32)));
;     }
;   }
;   __syncthreads();
.LBB0_99:
	v_and_b32_e32 v1, 64, v185
	v_xor_b32_e32 v0, 16, v185
	v_add_u32_e32 v1, 64, v1
	v_cmp_lt_i32_e32 vcc, v0, v1
	v_xor_b32_e32 v2, 32, v185
	v_readlane_b32 s64, v252, 4
	v_cndmask_b32_e32 v0, v185, v0, vcc
	v_lshlrev_b32_e32 v10, 2, v0
	ds_bpermute_b32 v0, v10, v124
	v_cmp_lt_i32_e32 vcc, v2, v1
	v_readlane_b32 s76, v252, 16
	v_readlane_b32 s77, v252, 17
	v_cndmask_b32_e32 v1, v185, v2, vcc
	v_lshlrev_b32_e32 v11, 2, v1
	s_waitcnt lgkmcnt(0)
	v_add_f32_e32 v0, v124, v0
	ds_bpermute_b32 v1, v11, v0
	v_or_b32_e32 v2, s41, v165
	v_add_u32_e32 v5, v2, v216
	v_readlane_b32 s65, v252, 5
	v_readlane_b32 s66, v252, 6
	s_waitcnt lgkmcnt(0)
	v_add_f32_e32 v0, v0, v1
	v_div_scale_f32 v1, s[14:15], v0, v0, 1.0
	v_rcp_f32_e32 v3, v1
	v_div_scale_f32 v2, vcc, 1.0, v0, 1.0
	v_readlane_b32 s67, v252, 7
	v_fma_f32 v4, -v1, v3, 1.0
	v_fmac_f32_e32 v3, v4, v3
	v_mul_f32_e32 v4, v2, v3
	v_fma_f32 v6, -v1, v4, v2
	v_fmac_f32_e32 v4, v6, v3
	v_fma_f32 v1, -v1, v4, v2
	v_div_fmas_f32 v1, v1, v3, v4
	v_div_fixup_f32 v4, v1, v0, 1.0
	v_ashrrev_i32_e32 v0, 2, v5
	v_and_b32_e32 v0, 0xffffffe0, v0
	v_lshl_or_b32 v12, s43, 1, v0
	v_or_b32_e32 v6, 16, v12
	v_pk_mul_f32 v[0:1], v[116:117], v[4:5] op_sel_hi:[1,0]
	v_pk_mul_f32 v[2:3], v[118:119], v[4:5] op_sel_hi:[1,0]
	v_ashrrev_i32_e32 v7, 31, v6
	v_cvt_pk_bf16_f32 v0, v0, v1
	v_cvt_pk_bf16_f32 v1, v2, v3
	v_pk_mul_f32 v[2:3], v[112:113], v[4:5] op_sel_hi:[1,0]
	v_pk_mul_f32 v[8:9], v[114:115], v[4:5] op_sel_hi:[1,0]
	v_lshlrev_b64 v[6:7], 13, v[6:7]
	v_lshlrev_b32_e32 v5, 6, v5
	v_lshl_add_u64 v[6:7], s[76:77], 0, v[6:7]
	v_and_b32_e32 v152, 0x1fc0, v5
	v_cvt_pk_bf16_f32 v2, v2, v3
	v_cvt_pk_bf16_f32 v3, v8, v9
	v_lshl_add_u64 v[6:7], v[6:7], 0, v[152:153]
	v_lshlrev_b32_e32 v8, 1, v164
	v_mov_b32_e32 v9, v153
	v_permlane16_swap_b32_e32 v0, v2
	v_permlane16_swap_b32_e32 v1, v3
	v_lshl_add_u64 v[6:7], v[6:7], 0, v[8:9]
	global_store_dwordx4 v[6:7], v[0:3], off nt
	v_readlane_b32 s68, v252, 8
	v_readlane_b32 s69, v252, 9
	v_pk_mul_f32 v[0:1], v[104:105], v[4:5] op_sel_hi:[1,0]
	v_pk_mul_f32 v[2:3], v[106:107], v[4:5] op_sel_hi:[1,0]
	v_cvt_pk_bf16_f32 v0, v0, v1
	v_cvt_pk_bf16_f32 v1, v2, v3
	v_pk_mul_f32 v[2:3], v[108:109], v[4:5] op_sel_hi:[1,0]
	v_pk_mul_f32 v[4:5], v[110:111], v[4:5] op_sel_hi:[1,0]
	v_cvt_pk_bf16_f32 v2, v2, v3
	v_cvt_pk_bf16_f32 v3, v4, v5
	ds_bpermute_b32 v4, v10, v125
	v_permlane16_swap_b32_e32 v0, v2
	v_permlane16_swap_b32_e32 v1, v3
	s_waitcnt lgkmcnt(0)
	v_add_f32_e32 v10, v125, v4
	ds_bpermute_b32 v11, v11, v10
	v_or_b32_e32 v4, 17, v12
	v_ashrrev_i32_e32 v5, 31, v4
	v_lshlrev_b64 v[4:5], 13, v[4:5]
	v_lshl_add_u64 v[4:5], s[76:77], 0, v[4:5]
	s_waitcnt lgkmcnt(0)
	v_add_f32_e32 v10, v10, v11
	v_div_scale_f32 v11, s[14:15], v10, v10, 1.0
	v_rcp_f32_e32 v12, v11
	v_lshl_add_u64 v[4:5], v[4:5], 0, v[152:153]
	v_lshl_add_u64 v[4:5], v[4:5], 0, v[8:9]
	global_store_dwordx4 v[4:5], v[0:3], off nt
	v_readlane_b32 s70, v252, 10
	v_readlane_b32 s71, v252, 11
	v_fma_f32 v0, -v11, v12, 1.0
	v_fmac_f32_e32 v12, v0, v12
	v_div_scale_f32 v0, vcc, 1.0, v10, 1.0
	v_mul_f32_e32 v1, v0, v12
	v_fma_f32 v2, -v11, v1, v0
	v_fmac_f32_e32 v1, v2, v12
	v_fma_f32 v0, -v11, v1, v0
	v_div_fmas_f32 v0, v0, v12, v1
	v_div_fixup_f32 v8, v0, v10, 1.0
	v_pk_mul_f32 v[0:1], v[100:101], v[8:9] op_sel_hi:[1,0]
	v_pk_mul_f32 v[2:3], v[102:103], v[8:9] op_sel_hi:[1,0]
	v_cvt_pk_bf16_f32 v0, v0, v1
	v_cvt_pk_bf16_f32 v1, v2, v3
	v_pk_mul_f32 v[2:3], v[96:97], v[8:9] op_sel_hi:[1,0]
	v_pk_mul_f32 v[10:11], v[98:99], v[8:9] op_sel_hi:[1,0]
	v_cvt_pk_bf16_f32 v2, v2, v3
	v_cvt_pk_bf16_f32 v3, v10, v11
	s_nop 0
	v_permlane16_swap_b32_e32 v0, v2
	v_permlane16_swap_b32_e32 v1, v3
	global_store_dwordx4 v[6:7], v[0:3], off offset:1024 nt
	v_pk_mul_f32 v[6:7], v[94:95], v[8:9] op_sel_hi:[1,0]
	v_readlane_b32 s72, v252, 12
	v_pk_mul_f32 v[0:1], v[88:89], v[8:9] op_sel_hi:[1,0]
	v_pk_mul_f32 v[2:3], v[90:91], v[8:9] op_sel_hi:[1,0]
	v_cvt_pk_bf16_f32 v0, v0, v1
	v_cvt_pk_bf16_f32 v1, v2, v3
	v_pk_mul_f32 v[2:3], v[92:93], v[8:9] op_sel_hi:[1,0]
	v_readlane_b32 s73, v252, 13
	v_cvt_pk_bf16_f32 v2, v2, v3
	v_cvt_pk_bf16_f32 v3, v6, v7
	s_nop 0
	v_permlane16_swap_b32_e32 v0, v2
	v_permlane16_swap_b32_e32 v1, v3
	v_readlane_b32 s74, v252, 14
	v_readlane_b32 s75, v252, 15
	v_readlane_b32 s78, v252, 18
	v_readlane_b32 s79, v252, 19
	global_store_dwordx4 v[4:5], v[0:3], off offset:1024 nt
	s_barrier

; __device__ __forceinline__ int widen_off(int fq) { return ((fq & 1) << 4) + ((fq >> 1) << 3); }
; template <int NW>
; __device__ __forceinline__ void attn_item(const Params& p, int seq_t0, int L, int h, int q0, unsigned char* smem,
;                                           const int tid) {
;     ...
; #pragma unroll
;   for (int rs = 0; rs < 2; ++rs) {
;     float l = red_fq(lrun[rs]);
;     float inv = 1.0f / l;
;     const int t = q0 + wid * 32 + rs * 16 + fr;
; #pragma unroll
;     for (int dp = 0; dp < 2; ++dp) {
;       const bf16x4 a = pack4(o[rs][2 * dp][0] * inv, o[rs][2 * dp][1] * inv, o[rs][2 * dp][2] * inv, o[rs][2 * dp][3] * inv);
;       const bf16x4 b = pack4(o[rs][2 * dp + 1][0] * inv, o[rs][2 * dp + 1][1] * inv, o[rs][2 * dp + 1][2] * inv,
;                              o[rs][2 * dp + 1][3] * inv);
;       __builtin_nontemporal_store(widen_pair(a, b), reinterpret_cast<u32x4*>(p.mix + blk(t, 512 + h * 64 + dp * 32 + widen_off(fq), 32)));
;     }
;   }
;   __syncthreads();
.LBB0_148:
	v_and_b32_e32 v1, 64, v185
	v_xor_b32_e32 v0, 16, v185
	v_add_u32_e32 v1, 64, v1
	v_cmp_lt_i32_e32 vcc, v0, v1
	v_xor_b32_e32 v2, 32, v185
	v_readlane_b32 s64, v252, 4
	v_cndmask_b32_e32 v0, v185, v0, vcc
	v_lshlrev_b32_e32 v10, 2, v0
	ds_bpermute_b32 v0, v10, v124
	v_cmp_lt_i32_e32 vcc, v2, v1
	v_readlane_b32 s76, v252, 16
	v_readlane_b32 s77, v252, 17
	v_cndmask_b32_e32 v1, v185, v2, vcc
	v_lshlrev_b32_e32 v11, 2, v1
	s_waitcnt lgkmcnt(0)
	v_add_f32_e32 v0, v124, v0
	ds_bpermute_b32 v1, v11, v0
	v_or_b32_e32 v2, s47, v165
	v_add_u32_e32 v5, v2, v216
	v_readlane_b32 s65, v252, 5
	v_readlane_b32 s66, v252, 6
	s_waitcnt lgkmcnt(0)
	v_add_f32_e32 v0, v0, v1
	v_div_scale_f32 v1, s[14:15], v0, v0, 1.0
	v_rcp_f32_e32 v3, v1
	v_div_scale_f32 v2, vcc, 1.0, v0, 1.0
	v_readlane_b32 s67, v252, 7
	v_fma_f32 v4, -v1, v3, 1.0
	v_fmac_f32_e32 v3, v4, v3
	v_mul_f32_e32 v4, v2, v3
	v_fma_f32 v6, -v1, v4, v2
	v_fmac_f32_e32 v4, v6, v3
	v_fma_f32 v1, -v1, v4, v2
	v_div_fmas_f32 v1, v1, v3, v4
	v_div_fixup_f32 v4, v1, v0, 1.0
	v_ashrrev_i32_e32 v0, 2, v5
	v_and_b32_e32 v0, 0xffffffe0, v0
	v_lshl_or_b32 v12, s43, 1, v0
	v_or_b32_e32 v6, 16, v12
	v_pk_mul_f32 v[0:1], v[112:113], v[4:5] op_sel_hi:[1,0]
	v_pk_mul_f32 v[2:3], v[114:115], v[4:5] op_sel_hi:[1,0]
	v_ashrrev_i32_e32 v7, 31, v6
	v_cvt_pk_bf16_f32 v0, v0, v1
	v_cvt_pk_bf16_f32 v1, v2, v3
	v_pk_mul_f32 v[2:3], v[116:117], v[4:5] op_sel_hi:[1,0]
	v_pk_mul_f32 v[8:9], v[118:119], v[4:5] op_sel_hi:[1,0]
	v_lshlrev_b64 v[6:7], 13, v[6:7]
	v_lshlrev_b32_e32 v5, 6, v5
	v_lshl_add_u64 v[6:7], s[76:77], 0, v[6:7]
	v_and_b32_e32 v152, 0x1fc0, v5
	v_cvt_pk_bf16_f32 v2, v2, v3
	v_cvt_pk_bf16_f32 v3, v8, v9
	v_lshl_add_u64 v[6:7], v[6:7], 0, v[152:153]
	v_lshlrev_b32_e32 v8, 1, v164
	v_mov_b32_e32 v9, v153
	v_permlane16_swap_b32_e32 v0, v2
	v_permlane16_swap_b32_e32 v1, v3
	v_lshl_add_u64 v[6:7], v[6:7], 0, v[8:9]
	global_store_dwordx4 v[6:7], v[0:3], off nt
	v_readlane_b32 s68, v252, 8
	v_readlane_b32 s69, v252, 9
	v_pk_mul_f32 v[0:1], v[104:105], v[4:5] op_sel_hi:[1,0]
	v_pk_mul_f32 v[2:3], v[106:107], v[4:5] op_sel_hi:[1,0]
	v_cvt_pk_bf16_f32 v0, v0, v1
	v_cvt_pk_bf16_f32 v1, v2, v3
	v_pk_mul_f32 v[2:3], v[108:109], v[4:5] op_sel_hi:[1,0]
	v_pk_mul_f32 v[4:5], v[110:111], v[4:5] op_sel_hi:[1,0]
	v_cvt_pk_bf16_f32 v2, v2, v3
	v_cvt_pk_bf16_f32 v3, v4, v5
	ds_bpermute_b32 v4, v10, v125
	v_permlane16_swap_b32_e32 v0, v2
	v_permlane16_swap_b32_e32 v1, v3
	s_waitcnt lgkmcnt(0)
	v_add_f32_e32 v10, v125, v4
	ds_bpermute_b32 v11, v11, v10
	v_or_b32_e32 v4, 17, v12
	v_ashrrev_i32_e32 v5, 31, v4
	v_lshlrev_b64 v[4:5], 13, v[4:5]
	v_lshl_add_u64 v[4:5], s[76:77], 0, v[4:5]
	s_waitcnt lgkmcnt(0)
	v_add_f32_e32 v10, v10, v11
	v_div_scale_f32 v11, s[14:15], v10, v10, 1.0
	v_rcp_f32_e32 v12, v11
	v_lshl_add_u64 v[4:5], v[4:5], 0, v[152:153]
	v_lshl_add_u64 v[4:5], v[4:5], 0, v[8:9]
	global_store_dwordx4 v[4:5], v[0:3], off nt
	s_mov_b64 s[14:15], 0
	v_readlane_b32 s70, v252, 10
	v_fma_f32 v0, -v11, v12, 1.0
	v_fmac_f32_e32 v12, v0, v12
	v_div_scale_f32 v0, vcc, 1.0, v10, 1.0
	v_mul_f32_e32 v1, v0, v12
	v_fma_f32 v2, -v11, v1, v0
	v_fmac_f32_e32 v1, v2, v12
	v_fma_f32 v0, -v11, v1, v0
	v_div_fmas_f32 v0, v0, v12, v1
	v_div_fixup_f32 v8, v0, v10, 1.0
	v_pk_mul_f32 v[0:1], v[88:89], v[8:9] op_sel_hi:[1,0]
	v_pk_mul_f32 v[2:3], v[90:91], v[8:9] op_sel_hi:[1,0]
	v_cvt_pk_bf16_f32 v0, v0, v1
	v_cvt_pk_bf16_f32 v1, v2, v3
	v_pk_mul_f32 v[2:3], v[100:101], v[8:9] op_sel_hi:[1,0]
	v_pk_mul_f32 v[10:11], v[102:103], v[8:9] op_sel_hi:[1,0]
	v_cvt_pk_bf16_f32 v2, v2, v3
	v_cvt_pk_bf16_f32 v3, v10, v11
	s_nop 0
	v_permlane16_swap_b32_e32 v0, v2
	v_permlane16_swap_b32_e32 v1, v3
	global_store_dwordx4 v[6:7], v[0:3], off offset:1024 nt
	v_pk_mul_f32 v[6:7], v[98:99], v[8:9] op_sel_hi:[1,0]
	v_readlane_b32 s71, v252, 11
	v_pk_mul_f32 v[0:1], v[92:93], v[8:9] op_sel_hi:[1,0]
	v_pk_mul_f32 v[2:3], v[94:95], v[8:9] op_sel_hi:[1,0]
	v_cvt_pk_bf16_f32 v0, v0, v1
	v_cvt_pk_bf16_f32 v1, v2, v3
	v_pk_mul_f32 v[2:3], v[96:97], v[8:9] op_sel_hi:[1,0]
	v_readlane_b32 s72, v252, 12
	v_cvt_pk_bf16_f32 v2, v2, v3
	v_cvt_pk_bf16_f32 v3, v6, v7
	s_nop 0
	v_permlane16_swap_b32_e32 v0, v2
	v_permlane16_swap_b32_e32 v1, v3
	v_readlane_b32 s73, v252, 13
	v_readlane_b32 s74, v252, 14
	v_readlane_b32 s75, v252, 15
	v_readlane_b32 s78, v252, 18
	v_readlane_b32 s79, v252, 19
	global_store_dwordx4 v[4:5], v[0:3], off offset:1024 nt
	s_barrier
